# FFN-up GEMM: the lagging wave half runs its tile epilogue before the tile's last rendezvous barrier, so the two halves' epilogues overlap instead of running one after the other
# speedup vs baseline: 1.0151x; 1.0008x over previous
.LBB0_1261:
	s_mov_b32 s50, 0
	v_readlane_b32 s0, v251, 36
	s_mov_b32 s22, s91
	v_readlane_b32 s4, v252, 47
	s_waitcnt vmcnt(0)
	v_lshl_add_u32 v8, s0, 6, v220
	s_and_b32 s0, s91, 63
	s_add_i32 s1, s0, -1
	s_cmp_lt_u32 s1, 5
	s_cbranch_scc0 .Lupr0_done
	s_sub_i32 s1, s91, s0
	s_lshl_b32 s0, s0, 8
	s_add_i32 s1, s1, s0
	s_cmpk_gt_i32 s1, 0x595
	s_cbranch_scc1 .Lupr0_done
	s_mov_b32 s22, s1

.LBB0_1276:
	s_add_u32 s16, s14, 0x100
	s_addc_u32 s17, s15, 0
	s_add_i32 s39, 0, 0x10000
	v_add_u32_e32 v152, s39, v137
	ds_read_b128 v[140:143], v152
	ds_read_b128 v[148:151], v152 offset:2048
	ds_read_b128 v[144:147], v152 offset:1024
	ds_read_b128 v[152:155], v152 offset:3072
	s_cmp_eq_u32 s38, 12
	s_cselect_b32 s21, s11, s17
	s_cselect_b32 s20, s10, s16
	s_cselect_b32 s19, s13, s37
	s_cselect_b32 s18, s12, s3
	v_lshl_add_u64 v[188:189], s[14:15], 0, v[132:133]
	s_add_i32 m0, s9, 0xc000
	ds_read_b128 v[156:159], v139
	ds_read_b128 v[164:167], v139 offset:2048
	ds_read_b128 v[172:175], v139 offset:4096
	ds_read_b128 v[180:183], v139 offset:6144
	ds_read_b128 v[160:163], v139 offset:1024
	ds_read_b128 v[168:171], v139 offset:3072
	ds_read_b128 v[176:179], v139 offset:5120
	ds_read_b128 v[184:187], v139 offset:7168
	global_load_lds_dwordx4 v[188:189], off
	v_lshl_add_u64 v[188:189], s[14:15], 0, v[134:135]
	s_add_i32 m0, s9, 0xe000
	s_nop 0
	global_load_lds_dwordx4 v[188:189], off
	s_waitcnt lgkmcnt(8)
	s_barrier
	s_waitcnt lgkmcnt(7)
	s_setprio 1
	v_mfma_f32_16x16x32_f16 v[126:129], v[140:143], v[156:159], v[126:129]
	v_mfma_f32_16x16x32_f16 v[122:125], v[148:151], v[156:159], v[122:125]
	s_waitcnt lgkmcnt(6)
	v_mfma_f32_16x16x32_f16 v[110:113], v[140:143], v[164:167], v[110:113]
	v_mfma_f32_16x16x32_f16 v[106:109], v[148:151], v[164:167], v[106:109]
	s_waitcnt lgkmcnt(5)
	v_mfma_f32_16x16x32_f16 v[94:97], v[140:143], v[172:175], v[94:97]
	v_mfma_f32_16x16x32_f16 v[90:93], v[148:151], v[172:175], v[90:93]
	s_waitcnt lgkmcnt(4)
	v_mfma_f32_16x16x32_f16 v[78:81], v[140:143], v[180:183], v[78:81]
	v_mfma_f32_16x16x32_f16 v[74:77], v[148:151], v[180:183], v[74:77]
	s_waitcnt lgkmcnt(3)
	v_mfma_f32_16x16x32_f16 v[126:129], v[144:147], v[160:163], v[126:129]
	v_mfma_f32_16x16x32_f16 v[122:125], v[152:155], v[160:163], v[122:125]
	s_waitcnt lgkmcnt(2)
	v_mfma_f32_16x16x32_f16 v[110:113], v[144:147], v[168:171], v[110:113]
	v_mfma_f32_16x16x32_f16 v[106:109], v[152:155], v[168:171], v[106:109]
	s_waitcnt lgkmcnt(1)
	v_mfma_f32_16x16x32_f16 v[94:97], v[144:147], v[176:179], v[94:97]
	v_mfma_f32_16x16x32_f16 v[90:93], v[152:155], v[176:179], v[90:93]
	s_waitcnt lgkmcnt(0)
	v_mfma_f32_16x16x32_f16 v[78:81], v[144:147], v[184:187], v[78:81]
	v_mfma_f32_16x16x32_f16 v[74:77], v[152:155], v[184:187], v[74:77]
	s_setprio 0
	s_barrier
	s_add_i32 s40, 0, 0x14000
	s_add_i32 s14, s39, s26
	v_add_u32_e32 v200, s40, v137
	v_lshl_add_u64 v[204:205], s[18:19], 0, v[32:33]
	s_mov_b32 m0, s14
	ds_read_b128 v[188:191], v200
	ds_read_b128 v[196:199], v200 offset:2048
	ds_read_b128 v[192:195], v200 offset:1024
	ds_read_b128 v[200:203], v200 offset:3072
	global_load_lds_dwordx4 v[204:205], off
	v_lshl_add_u64 v[206:207], s[18:19], 0, v[130:131]
	s_add_i32 m0, s14, 0x2000
	s_nop 0
	global_load_lds_dwordx4 v[206:207], off
	s_barrier
	s_waitcnt lgkmcnt(2)
	s_setprio 1
	v_mfma_f32_16x16x32_f16 v[118:121], v[188:191], v[156:159], v[118:121]
	v_mfma_f32_16x16x32_f16 v[114:117], v[196:199], v[156:159], v[114:117]
	v_mfma_f32_16x16x32_f16 v[102:105], v[188:191], v[164:167], v[102:105]
	v_mfma_f32_16x16x32_f16 v[98:101], v[196:199], v[164:167], v[98:101]
	v_mfma_f32_16x16x32_f16 v[86:89], v[188:191], v[172:175], v[86:89]
	v_mfma_f32_16x16x32_f16 v[82:85], v[196:199], v[172:175], v[82:85]
	v_mfma_f32_16x16x32_f16 v[70:73], v[188:191], v[180:183], v[70:73]
	v_mfma_f32_16x16x32_f16 v[66:69], v[196:199], v[180:183], v[66:69]
	s_waitcnt lgkmcnt(0)
	v_mfma_f32_16x16x32_f16 v[118:121], v[192:195], v[160:163], v[118:121]
	v_mfma_f32_16x16x32_f16 v[114:117], v[200:203], v[160:163], v[114:117]
	v_mfma_f32_16x16x32_f16 v[102:105], v[192:195], v[168:171], v[102:105]
	v_mfma_f32_16x16x32_f16 v[98:101], v[200:203], v[168:171], v[98:101]
	v_mfma_f32_16x16x32_f16 v[86:89], v[192:195], v[176:179], v[86:89]
	v_mfma_f32_16x16x32_f16 v[82:85], v[200:203], v[176:179], v[82:85]
	v_mfma_f32_16x16x32_f16 v[70:73], v[192:195], v[184:187], v[70:73]
	v_mfma_f32_16x16x32_f16 v[66:69], v[200:203], v[184:187], v[66:69]
	s_setprio 0
	s_mov_b32 m0, s9
	v_lshl_add_u64 v[208:209], s[20:21], 0, v[32:33]
	s_barrier
	ds_read_b128 v[156:159], v139 offset:16384
	ds_read_b128 v[164:167], v139 offset:18432
	ds_read_b128 v[172:175], v139 offset:20480
	ds_read_b128 v[180:183], v139 offset:22528
	ds_read_b128 v[160:163], v139 offset:17408
	ds_read_b128 v[168:171], v139 offset:19456
	ds_read_b128 v[176:179], v139 offset:21504
	ds_read_b128 v[184:187], v139 offset:23552
	global_load_lds_dwordx4 v[208:209], off
	v_lshl_add_u64 v[210:211], s[20:21], 0, v[130:131]
	s_mov_b32 m0, s27
	s_nop 0
	global_load_lds_dwordx4 v[210:211], off
	s_barrier
	s_waitcnt lgkmcnt(7)
	s_setprio 1
	v_mfma_f32_16x16x32_f16 v[62:65], v[140:143], v[156:159], v[62:65]
	v_mfma_f32_16x16x32_f16 v[58:61], v[148:151], v[156:159], v[58:61]
	s_waitcnt lgkmcnt(6)
	v_mfma_f32_16x16x32_f16 v[46:49], v[140:143], v[164:167], v[46:49]
	v_mfma_f32_16x16x32_f16 v[42:45], v[148:151], v[164:167], v[42:45]
	s_waitcnt lgkmcnt(5)
	v_mfma_f32_16x16x32_f16 v[28:31], v[140:143], v[172:175], v[28:31]
	v_mfma_f32_16x16x32_f16 v[24:27], v[148:151], v[172:175], v[24:27]
	s_waitcnt lgkmcnt(4)
	v_mfma_f32_16x16x32_f16 v[12:15], v[140:143], v[180:183], v[12:15]
	v_mfma_f32_16x16x32_f16 v[8:11], v[148:151], v[180:183], v[8:11]
	s_waitcnt lgkmcnt(3)
	v_mfma_f32_16x16x32_f16 v[62:65], v[144:147], v[160:163], v[62:65]
	v_mfma_f32_16x16x32_f16 v[58:61], v[152:155], v[160:163], v[58:61]
	s_waitcnt lgkmcnt(2)
	v_mfma_f32_16x16x32_f16 v[46:49], v[144:147], v[168:171], v[46:49]
	v_mfma_f32_16x16x32_f16 v[42:45], v[152:155], v[168:171], v[42:45]
	s_waitcnt lgkmcnt(1)
	v_mfma_f32_16x16x32_f16 v[28:31], v[144:147], v[176:179], v[28:31]
	v_mfma_f32_16x16x32_f16 v[24:27], v[152:155], v[176:179], v[24:27]
	s_waitcnt lgkmcnt(0)
	v_mfma_f32_16x16x32_f16 v[12:15], v[144:147], v[184:187], v[12:15]
	v_mfma_f32_16x16x32_f16 v[8:11], v[152:155], v[184:187], v[8:11]
	s_setprio 0
	s_barrier
	s_add_u32 s14, s18, 0x40000
	s_addc_u32 s15, s19, 0
	s_add_i32 s39, s40, s26
	v_lshl_add_u64 v[140:141], s[14:15], 0, v[32:33]
	s_mov_b32 m0, s39
	s_nop 0
	global_load_lds_dwordx4 v[140:141], off
	v_lshl_add_u64 v[140:141], s[14:15], 0, v[130:131]
	s_add_i32 m0, s39, 0x2000
	s_nop 0
	global_load_lds_dwordx4 v[140:141], off
	s_waitcnt vmcnt(6)
	s_barrier
	s_setprio 1
	v_mfma_f32_16x16x32_f16 v[54:57], v[188:191], v[156:159], v[54:57]
	v_mfma_f32_16x16x32_f16 v[50:53], v[196:199], v[156:159], v[50:53]
	v_mfma_f32_16x16x32_f16 v[38:41], v[188:191], v[164:167], v[38:41]
	v_mfma_f32_16x16x32_f16 v[34:37], v[196:199], v[164:167], v[34:37]
	v_mfma_f32_16x16x32_f16 v[20:23], v[188:191], v[172:175], v[20:23]
	v_mfma_f32_16x16x32_f16 v[16:19], v[196:199], v[172:175], v[16:19]
	v_mfma_f32_16x16x32_f16 v[4:7], v[188:191], v[180:183], v[4:7]
	v_mfma_f32_16x16x32_f16 v[0:3], v[196:199], v[180:183], v[0:3]
	v_mfma_f32_16x16x32_f16 v[54:57], v[192:195], v[160:163], v[54:57]
	v_mfma_f32_16x16x32_f16 v[50:53], v[200:203], v[160:163], v[50:53]
	v_mfma_f32_16x16x32_f16 v[38:41], v[192:195], v[168:171], v[38:41]
	v_mfma_f32_16x16x32_f16 v[34:37], v[200:203], v[168:171], v[34:37]
	v_mfma_f32_16x16x32_f16 v[20:23], v[192:195], v[176:179], v[20:23]
	v_mfma_f32_16x16x32_f16 v[16:19], v[200:203], v[176:179], v[16:19]
	v_mfma_f32_16x16x32_f16 v[4:7], v[192:195], v[184:187], v[4:7]
	v_mfma_f32_16x16x32_f16 v[0:3], v[200:203], v[184:187], v[0:3]
	s_setprio 0
	s_add_i32 s39, 0, 0x18000
	v_add_u32_e32 v152, s39, v137
	s_barrier
	ds_read_b128 v[140:143], v152
	ds_read_b128 v[148:151], v152 offset:2048
	ds_read_b128 v[144:147], v152 offset:1024
	ds_read_b128 v[152:155], v152 offset:3072
	s_add_u32 s14, s20, 0x40000
	s_addc_u32 s15, s21, 0
	s_mov_b32 m0, s28
	v_lshl_add_u64 v[188:189], s[14:15], 0, v[32:33]
	ds_read_b128 v[156:159], v139 offset:32768
	ds_read_b128 v[164:167], v139 offset:34816
	ds_read_b128 v[172:175], v139 offset:36864
	ds_read_b128 v[180:183], v139 offset:38912
	ds_read_b128 v[160:163], v139 offset:33792
	ds_read_b128 v[168:171], v139 offset:35840
	ds_read_b128 v[176:179], v139 offset:37888
	ds_read_b128 v[184:187], v139 offset:39936
	global_load_lds_dwordx4 v[188:189], off
	v_lshl_add_u64 v[188:189], s[14:15], 0, v[130:131]
	s_mov_b32 m0, s29
	s_nop 0
	global_load_lds_dwordx4 v[188:189], off
	s_waitcnt lgkmcnt(8)
	s_barrier
	s_waitcnt lgkmcnt(7)
	s_setprio 1
	v_mfma_f32_16x16x32_f16 v[126:129], v[140:143], v[156:159], v[126:129]
	v_mfma_f32_16x16x32_f16 v[122:125], v[148:151], v[156:159], v[122:125]
	s_waitcnt lgkmcnt(6)
	v_mfma_f32_16x16x32_f16 v[110:113], v[140:143], v[164:167], v[110:113]
	v_mfma_f32_16x16x32_f16 v[106:109], v[148:151], v[164:167], v[106:109]
	s_waitcnt lgkmcnt(5)
	v_mfma_f32_16x16x32_f16 v[94:97], v[140:143], v[172:175], v[94:97]
	v_mfma_f32_16x16x32_f16 v[90:93], v[148:151], v[172:175], v[90:93]
	s_waitcnt lgkmcnt(4)
	v_mfma_f32_16x16x32_f16 v[78:81], v[140:143], v[180:183], v[78:81]
	v_mfma_f32_16x16x32_f16 v[74:77], v[148:151], v[180:183], v[74:77]
	s_waitcnt lgkmcnt(3)
	v_mfma_f32_16x16x32_f16 v[126:129], v[144:147], v[160:163], v[126:129]
	v_mfma_f32_16x16x32_f16 v[122:125], v[152:155], v[160:163], v[122:125]
	s_waitcnt lgkmcnt(2)
	v_mfma_f32_16x16x32_f16 v[110:113], v[144:147], v[168:171], v[110:113]
	v_mfma_f32_16x16x32_f16 v[106:109], v[152:155], v[168:171], v[106:109]
	s_waitcnt lgkmcnt(1)
	v_mfma_f32_16x16x32_f16 v[94:97], v[144:147], v[176:179], v[94:97]
	v_mfma_f32_16x16x32_f16 v[90:93], v[152:155], v[176:179], v[90:93]
	s_waitcnt lgkmcnt(0)
	v_mfma_f32_16x16x32_f16 v[78:81], v[144:147], v[184:187], v[78:81]
	v_mfma_f32_16x16x32_f16 v[74:77], v[152:155], v[184:187], v[74:77]
	s_setprio 0
	s_barrier
	s_add_i32 s20, 0, 0x1c000
	s_add_i32 s14, s39, s26
	v_add_u32_e32 v200, s20, v137
	v_lshl_add_u64 v[204:205], v[204:205], 0, s[84:85]
	s_mov_b32 m0, s14
	ds_read_b128 v[188:191], v200
	ds_read_b128 v[196:199], v200 offset:2048
	ds_read_b128 v[192:195], v200 offset:1024
	ds_read_b128 v[200:203], v200 offset:3072
	global_load_lds_dwordx4 v[204:205], off
	v_lshl_add_u64 v[204:205], v[206:207], 0, s[84:85]
	s_add_i32 m0, s14, 0x2000
	s_nop 0
	global_load_lds_dwordx4 v[204:205], off
	s_barrier
	s_waitcnt lgkmcnt(2)
	s_setprio 1
	v_mfma_f32_16x16x32_f16 v[118:121], v[188:191], v[156:159], v[118:121]
	v_mfma_f32_16x16x32_f16 v[114:117], v[196:199], v[156:159], v[114:117]
	v_mfma_f32_16x16x32_f16 v[102:105], v[188:191], v[164:167], v[102:105]
	v_mfma_f32_16x16x32_f16 v[98:101], v[196:199], v[164:167], v[98:101]
	v_mfma_f32_16x16x32_f16 v[86:89], v[188:191], v[172:175], v[86:89]
	v_mfma_f32_16x16x32_f16 v[82:85], v[196:199], v[172:175], v[82:85]
	v_mfma_f32_16x16x32_f16 v[70:73], v[188:191], v[180:183], v[70:73]
	v_mfma_f32_16x16x32_f16 v[66:69], v[196:199], v[180:183], v[66:69]
	s_waitcnt lgkmcnt(0)
	v_mfma_f32_16x16x32_f16 v[118:121], v[192:195], v[160:163], v[118:121]
	v_mfma_f32_16x16x32_f16 v[114:117], v[200:203], v[160:163], v[114:117]
	v_mfma_f32_16x16x32_f16 v[102:105], v[192:195], v[168:171], v[102:105]
	v_mfma_f32_16x16x32_f16 v[98:101], v[200:203], v[168:171], v[98:101]
	v_mfma_f32_16x16x32_f16 v[86:89], v[192:195], v[176:179], v[86:89]
	v_mfma_f32_16x16x32_f16 v[82:85], v[200:203], v[176:179], v[82:85]
	v_mfma_f32_16x16x32_f16 v[70:73], v[192:195], v[184:187], v[70:73]
	v_mfma_f32_16x16x32_f16 v[66:69], v[200:203], v[184:187], v[66:69]
	s_setprio 0
	s_mov_b32 m0, s30
	v_lshl_add_u64 v[204:205], v[208:209], 0, s[84:85]
	s_barrier
	ds_read_b128 v[156:159], v139 offset:49152
	ds_read_b128 v[164:167], v139 offset:51200
	ds_read_b128 v[172:175], v139 offset:53248
	ds_read_b128 v[180:183], v139 offset:55296
	ds_read_b128 v[160:163], v139 offset:50176
	ds_read_b128 v[168:171], v139 offset:52224
	ds_read_b128 v[176:179], v139 offset:54272
	ds_read_b128 v[184:187], v139 offset:56320
	global_load_lds_dwordx4 v[204:205], off
	v_lshl_add_u64 v[204:205], v[210:211], 0, s[84:85]
	s_mov_b32 m0, s31
	s_nop 0
	global_load_lds_dwordx4 v[204:205], off
	s_barrier
	s_waitcnt lgkmcnt(7)
	s_setprio 1
	v_mfma_f32_16x16x32_f16 v[62:65], v[140:143], v[156:159], v[62:65]
	v_mfma_f32_16x16x32_f16 v[58:61], v[148:151], v[156:159], v[58:61]
	s_waitcnt lgkmcnt(6)
	v_mfma_f32_16x16x32_f16 v[46:49], v[140:143], v[164:167], v[46:49]
	v_mfma_f32_16x16x32_f16 v[42:45], v[148:151], v[164:167], v[42:45]
	s_waitcnt lgkmcnt(5)
	v_mfma_f32_16x16x32_f16 v[28:31], v[140:143], v[172:175], v[28:31]
	v_mfma_f32_16x16x32_f16 v[24:27], v[148:151], v[172:175], v[24:27]
	s_waitcnt lgkmcnt(4)
	v_mfma_f32_16x16x32_f16 v[12:15], v[140:143], v[180:183], v[12:15]
	v_mfma_f32_16x16x32_f16 v[8:11], v[148:151], v[180:183], v[8:11]
	s_waitcnt lgkmcnt(3)
	v_mfma_f32_16x16x32_f16 v[62:65], v[144:147], v[160:163], v[62:65]
	v_mfma_f32_16x16x32_f16 v[58:61], v[152:155], v[160:163], v[58:61]
	s_waitcnt lgkmcnt(2)
	v_mfma_f32_16x16x32_f16 v[46:49], v[144:147], v[168:171], v[46:49]
	v_mfma_f32_16x16x32_f16 v[42:45], v[152:155], v[168:171], v[42:45]
	s_waitcnt lgkmcnt(1)
	v_mfma_f32_16x16x32_f16 v[28:31], v[144:147], v[176:179], v[28:31]
	v_mfma_f32_16x16x32_f16 v[24:27], v[152:155], v[176:179], v[24:27]
	s_waitcnt lgkmcnt(0)
	v_mfma_f32_16x16x32_f16 v[12:15], v[144:147], v[184:187], v[12:15]
	v_mfma_f32_16x16x32_f16 v[8:11], v[152:155], v[184:187], v[8:11]
	s_setprio 0
	s_barrier
	s_add_u32 s14, s18, 0x40080
	s_addc_u32 s15, s19, 0
	s_add_i32 s18, s20, s26
	v_lshl_add_u64 v[140:141], s[14:15], 0, v[32:33]
	s_mov_b32 m0, s18
	s_nop 0
	global_load_lds_dwordx4 v[140:141], off
	v_lshl_add_u64 v[140:141], s[14:15], 0, v[130:131]
	s_add_i32 m0, s18, 0x2000
	s_nop 0
	global_load_lds_dwordx4 v[140:141], off
	s_waitcnt vmcnt(6)
	s_barrier
	s_setprio 1
	v_mfma_f32_16x16x32_f16 v[54:57], v[188:191], v[156:159], v[54:57]
	v_mfma_f32_16x16x32_f16 v[50:53], v[196:199], v[156:159], v[50:53]
	v_mfma_f32_16x16x32_f16 v[38:41], v[188:191], v[164:167], v[38:41]
	v_mfma_f32_16x16x32_f16 v[34:37], v[196:199], v[164:167], v[34:37]
	v_mfma_f32_16x16x32_f16 v[20:23], v[188:191], v[172:175], v[20:23]
	v_mfma_f32_16x16x32_f16 v[16:19], v[196:199], v[172:175], v[16:19]
	v_mfma_f32_16x16x32_f16 v[4:7], v[188:191], v[180:183], v[4:7]
	v_mfma_f32_16x16x32_f16 v[0:3], v[196:199], v[180:183], v[0:3]
	v_mfma_f32_16x16x32_f16 v[54:57], v[192:195], v[160:163], v[54:57]
	v_mfma_f32_16x16x32_f16 v[50:53], v[200:203], v[160:163], v[50:53]
	v_mfma_f32_16x16x32_f16 v[38:41], v[192:195], v[168:171], v[38:41]
	v_mfma_f32_16x16x32_f16 v[34:37], v[200:203], v[168:171], v[34:37]
	v_mfma_f32_16x16x32_f16 v[20:23], v[192:195], v[176:179], v[20:23]
	v_mfma_f32_16x16x32_f16 v[16:19], v[200:203], v[176:179], v[16:19]
	v_mfma_f32_16x16x32_f16 v[4:7], v[192:195], v[184:187], v[4:7]
	v_mfma_f32_16x16x32_f16 v[0:3], v[200:203], v[184:187], v[0:3]
	s_setprio 0
	s_add_i32 s38, s38, 2
	s_add_u32 s3, s3, 0x100
	s_addc_u32 s37, s37, 0
	s_cmp_gt_u32 s38, 13
	s_mov_b64 s[14:15], s[16:17]
	s_cbranch_scc0 .Lepib_up_bar
	s_cmpk_gt_u32 s23, 0xff
	s_cbranch_scc0 .Lepib_up_barx
	s_mov_b32 s50, 1
	s_branch .Lepib_up_exit
.Lepib_up_barx:
	s_barrier
	s_branch .Lepib_up_exit

.Lepib_up_exit:
.Lpeelx4:
	v_mul_f32_e32 v144, 0xbfb8aa3b, v127
	v_mul_f32_e32 v141, 0xbfb8aa3b, v126
	v_exp_f32_e32 v145, v144
	v_mul_f32_e32 v144, 0xbfb8aa3b, v128
	v_exp_f32_e32 v141, v141
	v_exp_f32_e32 v146, v144
	v_mul_f32_e32 v144, 0xbfb8aa3b, v129
	v_exp_f32_e32 v147, v144
	v_mul_f32_e32 v144, 0xbfb8aa3b, v122
	v_exp_f32_e32 v148, v144
	v_mul_f32_e32 v144, 0xbfb8aa3b, v123
	v_exp_f32_e32 v149, v144
	v_mul_f32_e32 v144, 0xbfb8aa3b, v124
	v_exp_f32_e32 v150, v144
	v_mul_f32_e32 v144, 0xbfb8aa3b, v125
	v_add_f32_e32 v141, 1.0, v141
	v_exp_f32_e32 v151, v144
	v_rcp_f32_e32 v144, v141
	v_add_f32_e32 v141, 1.0, v145
	v_rcp_f32_e32 v145, v141
	v_add_f32_e32 v141, 1.0, v146
	v_rcp_f32_e32 v146, v141
	v_add_f32_e32 v141, 1.0, v147
	v_rcp_f32_e32 v147, v141
	v_add_f32_e32 v141, 1.0, v148
	v_rcp_f32_e32 v148, v141
	v_add_f32_e32 v141, 1.0, v149
	v_rcp_f32_e32 v149, v141
	v_add_f32_e32 v141, 1.0, v150
	v_rcp_f32_e32 v150, v141
	v_add_f32_e32 v141, 1.0, v151
	v_pk_mul_f32 v[126:127], v[126:127], v[144:145]
	v_rcp_f32_e32 v151, v141
	v_pk_mul_f32 v[118:119], v[126:127], v[118:119]
	v_pk_mul_f32 v[126:127], v[128:129], v[146:147]
	v_cvt_pk_f16_f32 v118, v118, v119
	v_pk_mul_f32 v[120:121], v[126:127], v[120:121]
	v_lshl_or_b32 v142, s36, 7, v138
	v_cvt_pk_f16_f32 v119, v120, v121
	v_pk_mul_f32 v[120:121], v[122:123], v[148:149]
	v_lshl_add_u32 v140, s8, 8, v136
	v_pk_mul_f32 v[114:115], v[120:121], v[114:115]
	v_ashrrev_i32_e32 v143, 31, v142
	v_cvt_pk_f16_f32 v120, v114, v115
	v_pk_mul_f32 v[114:115], v[124:125], v[150:151]
	s_movk_i32 s3, 0x1600
	v_pk_mul_f32 v[114:115], v[114:115], v[116:117]
	v_lshlrev_b64 v[116:117], 1, v[142:143]
	v_cvt_pk_f16_f32 v121, v114, v115
	v_mov_b64_e32 v[114:115], s[92:93]
	v_mad_i64_i32 v[122:123], s[10:11], v140, s3, v[114:115]
	v_lshl_add_u64 v[122:123], v[122:123], 0, v[116:117]
	global_store_dwordx4 v[122:123], v[118:121], off
	v_mul_f32_e32 v122, 0xbfb8aa3b, v106
	v_mul_f32_e32 v123, 0xbfb8aa3b, v107
	v_mul_f32_e32 v118, 0xbfb8aa3b, v110
	v_mul_f32_e32 v119, 0xbfb8aa3b, v111
	v_exp_f32_e32 v118, v118
	v_exp_f32_e32 v119, v119
	v_mul_f32_e32 v120, 0xbfb8aa3b, v112
	v_mul_f32_e32 v121, 0xbfb8aa3b, v113
	v_exp_f32_e32 v120, v120
	v_exp_f32_e32 v121, v121
	v_exp_f32_e32 v122, v122
	v_exp_f32_e32 v123, v123
	v_mul_f32_e32 v124, 0xbfb8aa3b, v108
	v_mul_f32_e32 v125, 0xbfb8aa3b, v109
	v_add_f32_e32 v118, 1.0, v118
	v_add_f32_e32 v119, 1.0, v119
	v_exp_f32_e32 v124, v124
	v_exp_f32_e32 v125, v125
	v_rcp_f32_e32 v118, v118
	v_rcp_f32_e32 v119, v119
	v_add_f32_e32 v120, 1.0, v120
	v_add_f32_e32 v121, 1.0, v121
	v_rcp_f32_e32 v120, v120
	v_rcp_f32_e32 v121, v121
	v_add_f32_e32 v122, 1.0, v122
	v_add_f32_e32 v123, 1.0, v123
	v_rcp_f32_e32 v122, v122
	v_rcp_f32_e32 v123, v123
	v_add_f32_e32 v124, 1.0, v124
	v_add_f32_e32 v125, 1.0, v125
	v_pk_mul_f32 v[110:111], v[110:111], v[118:119]
	v_rcp_f32_e32 v124, v124
	v_rcp_f32_e32 v125, v125
	v_pk_mul_f32 v[102:103], v[110:111], v[102:103]
	v_pk_mul_f32 v[110:111], v[112:113], v[120:121]
	v_cvt_pk_f16_f32 v102, v102, v103
	v_pk_mul_f32 v[104:105], v[110:111], v[104:105]
	s_and_b64 vcc, exec, s[0:1]
	v_cvt_pk_f16_f32 v103, v104, v105
	v_pk_mul_f32 v[104:105], v[106:107], v[122:123]
	s_mov_b32 s36, s35
	v_pk_mul_f32 v[98:99], v[104:105], v[98:99]
	s_mov_b32 s8, s2
	v_cvt_pk_f16_f32 v104, v98, v99
	v_pk_mul_f32 v[98:99], v[108:109], v[124:125]
	s_mov_b64 s[16:17], s[6:7]
	v_pk_mul_f32 v[98:99], v[98:99], v[100:101]
	v_mul_f32_e32 v100, 0xbfb8aa3b, v96
	v_cvt_pk_f16_f32 v105, v98, v99
	v_or_b32_e32 v98, 16, v140
	v_mad_i64_i32 v[98:99], s[10:11], v98, s3, v[114:115]
	v_lshl_add_u64 v[98:99], v[98:99], 0, v[116:117]
	global_store_dwordx4 v[98:99], v[102:105], off
	v_mul_f32_e32 v98, 0xbfb8aa3b, v94
	v_mul_f32_e32 v99, 0xbfb8aa3b, v95
	v_exp_f32_e32 v98, v98
	v_exp_f32_e32 v99, v99
	v_mul_f32_e32 v101, 0xbfb8aa3b, v97
	v_exp_f32_e32 v100, v100
	v_exp_f32_e32 v101, v101
	v_mul_f32_e32 v102, 0xbfb8aa3b, v90
	v_mul_f32_e32 v103, 0xbfb8aa3b, v91
	v_exp_f32_e32 v102, v102
	v_exp_f32_e32 v103, v103
	v_mul_f32_e32 v104, 0xbfb8aa3b, v92
	v_mul_f32_e32 v105, 0xbfb8aa3b, v93
	v_add_f32_e32 v98, 1.0, v98
	v_add_f32_e32 v99, 1.0, v99
	v_exp_f32_e32 v104, v104
	v_exp_f32_e32 v105, v105
	v_rcp_f32_e32 v98, v98
	v_rcp_f32_e32 v99, v99
	v_add_f32_e32 v100, 1.0, v100
	v_add_f32_e32 v101, 1.0, v101
	v_rcp_f32_e32 v100, v100
	v_rcp_f32_e32 v101, v101
	v_add_f32_e32 v102, 1.0, v102
	v_add_f32_e32 v103, 1.0, v103
	v_rcp_f32_e32 v102, v102
	v_rcp_f32_e32 v103, v103
	v_add_f32_e32 v104, 1.0, v104
	v_add_f32_e32 v105, 1.0, v105
	v_pk_mul_f32 v[94:95], v[94:95], v[98:99]
	v_rcp_f32_e32 v104, v104
	v_rcp_f32_e32 v105, v105
	v_pk_mul_f32 v[86:87], v[94:95], v[86:87]
	v_pk_mul_f32 v[94:95], v[96:97], v[100:101]
	v_cvt_pk_f16_f32 v86, v86, v87
	v_pk_mul_f32 v[88:89], v[94:95], v[88:89]
	s_mov_b64 s[14:15], s[4:5]
	v_cvt_pk_f16_f32 v87, v88, v89
	v_pk_mul_f32 v[88:89], v[90:91], v[102:103]
	s_nop 0
	v_pk_mul_f32 v[82:83], v[88:89], v[82:83]
	s_nop 0
	v_cvt_pk_f16_f32 v88, v82, v83
	v_pk_mul_f32 v[82:83], v[92:93], v[104:105]
	s_nop 0
	v_pk_mul_f32 v[82:83], v[82:83], v[84:85]
	v_mul_f32_e32 v84, 0xbfb8aa3b, v80
	v_cvt_pk_f16_f32 v89, v82, v83
	v_or_b32_e32 v82, 32, v140
	v_mad_i64_i32 v[82:83], s[10:11], v82, s3, v[114:115]
	v_lshl_add_u64 v[82:83], v[82:83], 0, v[116:117]
	global_store_dwordx4 v[82:83], v[86:89], off
	v_mul_f32_e32 v82, 0xbfb8aa3b, v78
	v_mul_f32_e32 v83, 0xbfb8aa3b, v79
	v_exp_f32_e32 v82, v82
	v_exp_f32_e32 v83, v83
	v_mul_f32_e32 v85, 0xbfb8aa3b, v81
	v_exp_f32_e32 v84, v84
	v_exp_f32_e32 v85, v85
	v_mul_f32_e32 v86, 0xbfb8aa3b, v74
	v_mul_f32_e32 v87, 0xbfb8aa3b, v75
	v_exp_f32_e32 v86, v86
	v_exp_f32_e32 v87, v87
	v_mul_f32_e32 v88, 0xbfb8aa3b, v76
	v_mul_f32_e32 v89, 0xbfb8aa3b, v77
	v_add_f32_e32 v82, 1.0, v82
	v_add_f32_e32 v83, 1.0, v83
	v_exp_f32_e32 v88, v88
	v_exp_f32_e32 v89, v89
	v_rcp_f32_e32 v82, v82
	v_rcp_f32_e32 v83, v83
	v_add_f32_e32 v84, 1.0, v84
	v_add_f32_e32 v85, 1.0, v85
	v_rcp_f32_e32 v84, v84
	v_rcp_f32_e32 v85, v85
	v_add_f32_e32 v86, 1.0, v86
	v_add_f32_e32 v87, 1.0, v87
	v_rcp_f32_e32 v86, v86
	v_rcp_f32_e32 v87, v87
	v_add_f32_e32 v88, 1.0, v88
	v_add_f32_e32 v89, 1.0, v89
	v_pk_mul_f32 v[78:79], v[78:79], v[82:83]
	v_rcp_f32_e32 v88, v88
	v_rcp_f32_e32 v89, v89
	v_pk_mul_f32 v[70:71], v[78:79], v[70:71]
	v_pk_mul_f32 v[78:79], v[80:81], v[84:85]
	v_cvt_pk_f16_f32 v70, v70, v71
	v_pk_mul_f32 v[72:73], v[78:79], v[72:73]
	s_nop 0
	v_cvt_pk_f16_f32 v71, v72, v73
	v_pk_mul_f32 v[72:73], v[74:75], v[86:87]
	v_add_u32_e32 v74, 0x80, v140
	v_pk_mul_f32 v[66:67], v[72:73], v[66:67]
	s_nop 0
	v_cvt_pk_f16_f32 v72, v66, v67
	v_pk_mul_f32 v[66:67], v[76:77], v[88:89]
	s_nop 0
	v_pk_mul_f32 v[66:67], v[66:67], v[68:69]
	v_mul_f32_e32 v68, 0xbfb8aa3b, v64
	v_cvt_pk_f16_f32 v73, v66, v67
	v_or_b32_e32 v66, 48, v140
	v_mad_i64_i32 v[66:67], s[10:11], v66, s3, v[114:115]
	v_lshl_add_u64 v[66:67], v[66:67], 0, v[116:117]
	global_store_dwordx4 v[66:67], v[70:73], off
	v_mul_f32_e32 v66, 0xbfb8aa3b, v62
	v_mul_f32_e32 v67, 0xbfb8aa3b, v63
	v_exp_f32_e32 v66, v66
	v_exp_f32_e32 v67, v67
	v_mul_f32_e32 v69, 0xbfb8aa3b, v65
	v_exp_f32_e32 v68, v68
	v_exp_f32_e32 v69, v69
	v_mul_f32_e32 v70, 0xbfb8aa3b, v58
	v_mul_f32_e32 v71, 0xbfb8aa3b, v59
	v_exp_f32_e32 v70, v70
	v_exp_f32_e32 v71, v71
	v_mul_f32_e32 v72, 0xbfb8aa3b, v60
	v_mul_f32_e32 v73, 0xbfb8aa3b, v61
	v_add_f32_e32 v66, 1.0, v66
	v_add_f32_e32 v67, 1.0, v67
	v_exp_f32_e32 v72, v72
	v_exp_f32_e32 v73, v73
	v_rcp_f32_e32 v66, v66
	v_rcp_f32_e32 v67, v67
	v_add_f32_e32 v68, 1.0, v68
	v_add_f32_e32 v69, 1.0, v69
	v_rcp_f32_e32 v68, v68
	v_rcp_f32_e32 v69, v69
	v_add_f32_e32 v70, 1.0, v70
	v_add_f32_e32 v71, 1.0, v71
	v_rcp_f32_e32 v70, v70
	v_rcp_f32_e32 v71, v71
	v_add_f32_e32 v72, 1.0, v72
	v_add_f32_e32 v73, 1.0, v73
	v_pk_mul_f32 v[62:63], v[62:63], v[66:67]
	v_rcp_f32_e32 v72, v72
	v_rcp_f32_e32 v73, v73
	v_pk_mul_f32 v[54:55], v[62:63], v[54:55]
	v_pk_mul_f32 v[62:63], v[64:65], v[68:69]
	v_cvt_pk_f16_f32 v54, v54, v55
	v_pk_mul_f32 v[56:57], v[62:63], v[56:57]
	s_nop 0
	v_cvt_pk_f16_f32 v55, v56, v57
	v_pk_mul_f32 v[56:57], v[58:59], v[70:71]
	s_nop 0
	v_pk_mul_f32 v[50:51], v[56:57], v[50:51]
	s_nop 0
	v_cvt_pk_f16_f32 v56, v50, v51
	v_pk_mul_f32 v[50:51], v[60:61], v[72:73]
	s_nop 0
	v_pk_mul_f32 v[50:51], v[50:51], v[52:53]
	v_mul_f32_e32 v52, 0xbfb8aa3b, v48
	v_cvt_pk_f16_f32 v57, v50, v51
	v_mad_i64_i32 v[50:51], s[10:11], v74, s3, v[114:115]
	v_lshl_add_u64 v[50:51], v[50:51], 0, v[116:117]
	global_store_dwordx4 v[50:51], v[54:57], off
	v_mul_f32_e32 v50, 0xbfb8aa3b, v46
	v_mul_f32_e32 v51, 0xbfb8aa3b, v47
	v_exp_f32_e32 v50, v50
	v_exp_f32_e32 v51, v51
	v_mul_f32_e32 v53, 0xbfb8aa3b, v49
	v_exp_f32_e32 v52, v52
	v_exp_f32_e32 v53, v53
	v_mul_f32_e32 v54, 0xbfb8aa3b, v42
	v_mul_f32_e32 v55, 0xbfb8aa3b, v43
	v_exp_f32_e32 v54, v54
	v_exp_f32_e32 v55, v55
	v_mul_f32_e32 v56, 0xbfb8aa3b, v44
	v_mul_f32_e32 v57, 0xbfb8aa3b, v45
	v_add_f32_e32 v50, 1.0, v50
	v_add_f32_e32 v51, 1.0, v51
	v_exp_f32_e32 v56, v56
	v_exp_f32_e32 v57, v57
	v_rcp_f32_e32 v50, v50
	v_rcp_f32_e32 v51, v51
	v_add_f32_e32 v52, 1.0, v52
	v_add_f32_e32 v53, 1.0, v53
	v_rcp_f32_e32 v52, v52
	v_rcp_f32_e32 v53, v53
	v_add_f32_e32 v54, 1.0, v54
	v_add_f32_e32 v55, 1.0, v55
	v_rcp_f32_e32 v54, v54
	v_rcp_f32_e32 v55, v55
	v_add_f32_e32 v56, 1.0, v56
	v_add_f32_e32 v57, 1.0, v57
	v_pk_mul_f32 v[46:47], v[46:47], v[50:51]
	v_rcp_f32_e32 v56, v56
	v_rcp_f32_e32 v57, v57
	v_pk_mul_f32 v[38:39], v[46:47], v[38:39]
	v_pk_mul_f32 v[46:47], v[48:49], v[52:53]
	v_cvt_pk_f16_f32 v38, v38, v39
	v_pk_mul_f32 v[40:41], v[46:47], v[40:41]
	s_nop 0
	v_cvt_pk_f16_f32 v39, v40, v41
	v_pk_mul_f32 v[40:41], v[42:43], v[54:55]
	s_nop 0
	v_pk_mul_f32 v[34:35], v[40:41], v[34:35]
	s_nop 0
	v_cvt_pk_f16_f32 v40, v34, v35
	v_pk_mul_f32 v[34:35], v[44:45], v[56:57]
	s_nop 0
	v_pk_mul_f32 v[34:35], v[34:35], v[36:37]
	v_mul_f32_e32 v36, 0xbfb8aa3b, v30
	v_cvt_pk_f16_f32 v41, v34, v35
	v_add_u32_e32 v34, 0x90, v140
	v_mad_i64_i32 v[34:35], s[10:11], v34, s3, v[114:115]
	v_lshl_add_u64 v[34:35], v[34:35], 0, v[116:117]
	global_store_dwordx4 v[34:35], v[38:41], off
	v_mul_f32_e32 v34, 0xbfb8aa3b, v28
	v_mul_f32_e32 v35, 0xbfb8aa3b, v29
	v_exp_f32_e32 v34, v34
	v_exp_f32_e32 v35, v35
	v_mul_f32_e32 v37, 0xbfb8aa3b, v31
	v_exp_f32_e32 v36, v36
	v_exp_f32_e32 v37, v37
	v_mul_f32_e32 v38, 0xbfb8aa3b, v24
	v_mul_f32_e32 v39, 0xbfb8aa3b, v25
	v_exp_f32_e32 v38, v38
	v_exp_f32_e32 v39, v39
	v_mul_f32_e32 v40, 0xbfb8aa3b, v26
	v_mul_f32_e32 v41, 0xbfb8aa3b, v27
	v_add_f32_e32 v34, 1.0, v34
	v_add_f32_e32 v35, 1.0, v35
	v_exp_f32_e32 v40, v40
	v_exp_f32_e32 v41, v41
	v_rcp_f32_e32 v34, v34
	v_rcp_f32_e32 v35, v35
	v_add_f32_e32 v36, 1.0, v36
	v_add_f32_e32 v37, 1.0, v37
	v_rcp_f32_e32 v36, v36
	v_rcp_f32_e32 v37, v37
	v_add_f32_e32 v38, 1.0, v38
	v_add_f32_e32 v39, 1.0, v39
	v_rcp_f32_e32 v38, v38
	v_rcp_f32_e32 v39, v39
	v_add_f32_e32 v40, 1.0, v40
	v_add_f32_e32 v41, 1.0, v41
	v_pk_mul_f32 v[28:29], v[28:29], v[34:35]
	v_rcp_f32_e32 v40, v40
	v_rcp_f32_e32 v41, v41
	v_pk_mul_f32 v[20:21], v[28:29], v[20:21]
	v_pk_mul_f32 v[28:29], v[30:31], v[36:37]
	v_cvt_pk_f16_f32 v20, v20, v21
	v_pk_mul_f32 v[22:23], v[28:29], v[22:23]
	s_nop 0
	v_cvt_pk_f16_f32 v21, v22, v23
	v_pk_mul_f32 v[22:23], v[24:25], v[38:39]
	s_nop 0
	v_pk_mul_f32 v[16:17], v[22:23], v[16:17]
	s_nop 0
	v_cvt_pk_f16_f32 v22, v16, v17
	v_pk_mul_f32 v[16:17], v[26:27], v[40:41]
	s_nop 0
	v_pk_mul_f32 v[16:17], v[16:17], v[18:19]
	v_mul_f32_e32 v18, 0xbfb8aa3b, v14
	v_cvt_pk_f16_f32 v23, v16, v17
	v_add_u32_e32 v16, 0xa0, v140
	v_mad_i64_i32 v[16:17], s[10:11], v16, s3, v[114:115]
	v_lshl_add_u64 v[16:17], v[16:17], 0, v[116:117]
	global_store_dwordx4 v[16:17], v[20:23], off
	v_mul_f32_e32 v16, 0xbfb8aa3b, v12
	v_mul_f32_e32 v17, 0xbfb8aa3b, v13
	v_exp_f32_e32 v16, v16
	v_exp_f32_e32 v17, v17
	v_mul_f32_e32 v19, 0xbfb8aa3b, v15
	v_exp_f32_e32 v18, v18
	v_exp_f32_e32 v19, v19
	v_mul_f32_e32 v20, 0xbfb8aa3b, v8
	v_mul_f32_e32 v21, 0xbfb8aa3b, v9
	v_exp_f32_e32 v20, v20
	v_exp_f32_e32 v21, v21
	v_mul_f32_e32 v22, 0xbfb8aa3b, v10
	v_mul_f32_e32 v23, 0xbfb8aa3b, v11
	v_add_f32_e32 v16, 1.0, v16
	v_add_f32_e32 v17, 1.0, v17
	v_exp_f32_e32 v22, v22
	v_exp_f32_e32 v23, v23
	v_rcp_f32_e32 v16, v16
	v_rcp_f32_e32 v17, v17
	v_add_f32_e32 v18, 1.0, v18
	v_add_f32_e32 v19, 1.0, v19
	v_rcp_f32_e32 v18, v18
	v_rcp_f32_e32 v19, v19
	v_add_f32_e32 v20, 1.0, v20
	v_add_f32_e32 v21, 1.0, v21
	v_rcp_f32_e32 v20, v20
	v_rcp_f32_e32 v21, v21
	v_add_f32_e32 v22, 1.0, v22
	v_add_f32_e32 v23, 1.0, v23
	v_pk_mul_f32 v[12:13], v[12:13], v[16:17]
	v_rcp_f32_e32 v22, v22
	v_rcp_f32_e32 v23, v23
	v_pk_mul_f32 v[4:5], v[12:13], v[4:5]
	v_pk_mul_f32 v[12:13], v[14:15], v[18:19]
	v_cvt_pk_f16_f32 v4, v4, v5
	v_pk_mul_f32 v[6:7], v[12:13], v[6:7]
	s_nop 0
	v_cvt_pk_f16_f32 v5, v6, v7
	v_pk_mul_f32 v[6:7], v[8:9], v[20:21]
	s_nop 0
	v_pk_mul_f32 v[0:1], v[6:7], v[0:1]
	s_nop 0
	v_cvt_pk_f16_f32 v6, v0, v1
	v_pk_mul_f32 v[0:1], v[10:11], v[22:23]
	s_nop 0
	v_pk_mul_f32 v[0:1], v[0:1], v[2:3]
	s_nop 0
	v_cvt_pk_f16_f32 v7, v0, v1
	v_add_u32_e32 v0, 0xb0, v140
	v_mad_i64_i32 v[0:1], s[10:11], v0, s3, v[114:115]
	v_lshl_add_u64 v[0:1], v[0:1], 0, v[116:117]
	global_store_dwordx4 v[0:1], v[4:7], off
	s_cmp_eq_u32 s50, 0
	s_cbranch_scc1 .Lepib_up_nb
	s_mov_b32 s50, 0
	s_barrier
.Lepib_up_nb:
	s_cmp_lg_u32 s34, 1
	s_cbranch_scc1 .Lups_skip
	s_and_b32 s0, s91, 63
	s_cmp_gt_u32 s0, 5
	s_cbranch_scc1 .Lups_skip
	s_cmp_gt_u32 s91, 196
	s_cbranch_scc1 .Lups_skip
	s_waitcnt vmcnt(0)
	s_barrier
	v_readlane_b32 s0, v251, 36
	s_cmp_lg_u32 s0, 0
	s_cbranch_scc1 .Lups_skip
	buffer_wbl2 sc1
	s_waitcnt vmcnt(0)
	v_readlane_b32 s2, v255, 45
	v_readlane_b32 s3, v254, 25
	s_lshl_b32 s2, s2, 1
	s_cmp_eq_u32 s3, 0
	s_cselect_b32 s3, 1, 0
	s_add_i32 s2, s2, s3
	s_lshl_b32 s2, s2, 2
	s_add_i32 s2, s2, 14016
	v_readlane_b32 s0, v251, 32
	v_readlane_b32 s1, v251, 33
	s_add_u32 s0, s0, s2
	s_addc_u32 s1, s1, 0
	s_mov_b64 s[2:3], exec
	s_mov_b64 exec, 1
	global_atomic_add v33, v248, s[0:1]
	s_mov_b64 exec, s[2:3]
